# dilated attention: skewed 4-step schedule (per-wave start tile), tiles 2,3 DMA before the loop, on top of vint+p0+p0b
# speedup vs baseline: 1.0078x; 1.0059x over previous
; #define DUPREP(k) for (int rep_ = 0; rep_ < 1 + ((MK_DUP >> (k)) & 1); ++rep_)
;     ...
;   const int tid = otid(), wid = __builtin_amdgcn_readfirstlane(tid >> 6), lane = tid & 63, r32 = lane & 31, hi = lane >> 5;
;   char* V_lds = lds + 4 * SHM_K; char* K_lds = lds;
;   float* ws = (float*)(lds + 4 * SHM_K + 4 * SHM_V) + wid * 64; float* li_l = ws; float* al_l = ws + 32;
;   float m_reg = -1e30f, l_reg = 0; f32x16 o[4] = {}; bf16x8 qr[8];
;   const bf16* Qw = Qb + (long)(wid * QBLK + r32) * qs + hi * 8;
; #pragma unroll
;   for (int d0 = 0; d0 < 8; ++d0) qr[d0] = St::ld8(Qw + d0 * 16);
;   const int vb0 = (int)(uintptr_t)V_lds + v_rd_base(lane);
;   const int kb = DIL ? i0 - 64 : 0;
;     ...
;   int krow[2], kcol[2], vrow[2], vcol[2];
; #pragma unroll
;   for (int i = 0; i < 2; ++i) { const int pc = 2 * wid + i;
;     krow[i] = pc * 4 + (lane >> 4); kcol[i] = (((lane & 15) ^ (krow[i] & 7)) << 3);
;     const int sub = pc * 2 + (lane >> 5), kk = ((sub >> 2) << 3) + ((lane & 31) >> 2);
;     vrow[i] = kk; vcol[i] = ((sub & 3) << 5) + ((lane & 3) << 3); }
;   unsigned kdo[2], vdo[2];
; #pragma unroll
;   for (int i = 0; i < 2; ++i) { kdo[i] = (unsigned)(krow[i] * (int)ks + kcol[i]); vdo[i] = (unsigned)(vrow[i] * (int)ks + vcol[i]); }
;     ...
;   f32x16 pA0, pA1, pB0, pB1; float mnA, mnB, alA, alB; bf16x8 pa0, pa1, pa2, pa3; const int NT = DIL ? 6 : seq / KVBLK;
;   DMA(0, 0); DMA(1, 1);
;   if constexpr (!DIL && MK_PP) { DMA(2, 2); asm volatile("s_waitcnt vmcnt(8)\n\ts_barrier" ::: "memory"); }
;   else asm volatile("s_waitcnt vmcnt(4)\n\ts_barrier" ::: "memory");
; __global__ void __launch_bounds__(512, 2) mk_fwd(Params p) {
;     ...
;                 DUPREP(3) for (int u = vcu; u < 1536; u += G) {
;                     const int pt = u >> 9, rem = u & 511, b = rem >> 8, h = (rem >> 5) & 7, w = rem & 31;
;                     const int d = (pt == 0) ? 1 : (pt == 1) ? 4 : 16, res = w & (d - 1), blk = w / d, i0 = blk * 256, nsub = T / d;
;                     const float slope = __builtin_amdgcn_exp2f(-(float)(h + 1));
;                     const float nslopeC = -slope * (float)d * att::LOG2E;
;                     const size_t tok0 = (size_t)b * T + res;
;                     const att::bf16* Pb = (const att::bf16*)PROJ + ((size_t)h * M + tok0) * HD;
;                     const long rs = (long)d * HD;
.LBB0_137:
	s_cmpk_gt_i32 s99, 0x5ff
	s_cbranch_scc1 .LBB0_157
	s_ashr_i32 s36, s99, 9
	s_bfe_u32 s9, s99, 0x30005
	s_and_b32 s8, s99, 31
	s_cmp_eq_u32 s36, 1
	s_cselect_b64 s[2:3], -1, 0
	s_and_b64 s[0:1], s[2:3], exec
	s_cselect_b32 s10, 4, 16
	s_cselect_b32 s11, 2, 4
	s_cselect_b32 s12, 9, 11
	s_cmpk_lt_u32 s99, 0x200
	s_cselect_b64 s[18:19], -1, 0
	s_and_b64 s[0:1], s[18:19], exec
	s_cselect_b32 s15, 1, s10
	s_cselect_b32 s0, 0, s11
	s_cselect_b32 s10, 7, s12
	s_add_i32 s1, s15, -1
	s_and_b32 s1, s1, s8
	s_lshr_b32 s8, s8, s0
	s_lshr_b32 s11, 0x2000, s0
	s_lshl_b32 s0, s99, 5
	s_and_b32 s0, s0, 0x2000
	s_lshl_b32 s40, s8, 8
	s_add_i32 s21, s9, 1
	s_or_b32 s52, s1, s0
	s_lshl_b32 s0, s9, 22
	s_add_u32 s0, s34, s0
	s_addc_u32 s1, s35, 0
	s_lshl_b32 s8, s52, 8
	s_mov_b32 s41, s53
	s_add_u32 s8, s0, s8
	s_addc_u32 s14, s1, 0
	s_lshl_b64 s[0:1], s[40:41], s10
	s_lshl_b64 s[0:1], s[0:1], 1
	s_add_u32 s12, s8, s0
	s_addc_u32 s13, s14, s1
	s_add_u32 s42, s8, 0x7000000
	s_addc_u32 s43, s14, 0
	v_mov_b32_e32 v10, v214
	s_add_u32 s0, s8, 0x9000000
	s_addc_u32 s1, s14, 0
	v_readfirstlane_b32 s23, v10
	s_ashr_i32 s8, s23, 6
	v_and_b32_e32 v141, 31, v10
	s_lshl_b32 s22, s8, 5
	v_or_b32_e32 v132, s22, v141
	v_ashrrev_i32_e32 v133, 31, v132
	v_bfe_u32 v142, v10, 5, 1
	v_lshlrev_b64 v[2:3], s10, v[132:133]
	v_lshl_add_u64 v[2:3], v[2:3], 1, s[12:13]
	v_lshlrev_b32_e32 v130, 4, v142
	v_mov_b32_e32 v131, v1
	v_lshl_add_u64 v[2:3], v[2:3], 0, v[130:131]
	s_mov_b64 s[12:13], 0x5000000
	v_lshl_add_u64 v[4:5], v[2:3], 0, s[12:13]
	s_mov_b32 s12, 0x5000000
	s_lshl_b32 s37, s8, 3
	v_bfe_u32 v131, v10, 4, 2
	v_add_co_u32_e32 v2, vcc, s12, v2
	v_lshlrev_b32_e32 v13, 3, v10
	v_or_b32_e32 v14, s37, v131
	v_and_b32_e32 v0, 32, v10
	s_sub_i32 s25, s40, 64
	v_addc_co_u32_e32 v3, vcc, 0, v3, vcc
	global_load_dwordx4 v[98:101], v[4:5], off offset:32
	global_load_dwordx4 v[102:105], v[4:5], off offset:64
	global_load_dwordx4 v[106:109], v[4:5], off offset:96
	global_load_dwordx4 v[110:113], v[4:5], off offset:128
	global_load_dwordx4 v[114:117], v[4:5], off offset:160
	global_load_dwordx4 v[118:121], v[4:5], off offset:192
	global_load_dwordx4 v[122:125], v[2:3], off
	global_load_dwordx4 v[126:129], v[4:5], off offset:224
	v_and_or_b32 v5, v13, 24, v0
	v_add_u32_e32 v0, s25, v14
	s_add_i32 s12, s11, -1
	v_max_i32_e32 v0, 0, v0
	v_min_u32_e32 v0, s12, v0
	v_bitop3_b32 v4, v131, v10, 15 bitop3:0x78
	s_lshl_b32 s38, s8, 11
	v_lshlrev_b64 v[2:3], s10, v[0:1]
	v_bfe_u32 v11, v10, 2, 3
	v_lshl_add_u64 v[2:3], v[2:3], 1, s[42:43]
	v_lshlrev_b32_e32 v0, 4, v4
	s_add_i32 s13, s38, 0
	v_or_b32_e32 v12, s37, v11
	v_lshl_add_u64 v[2:3], v[2:3], 0, v[0:1]
	s_mov_b32 m0, s13
	v_or_b32_e32 v15, 4, v14
	global_load_lds_dwordx4 v[2:3], off
	v_add_u32_e32 v2, s25, v12
	v_max_i32_e32 v2, 0, v2
	v_add_u32_e32 v6, s25, v15
	v_min_u32_e32 v2, s12, v2
	v_mov_b32_e32 v3, v1
	v_max_i32_e32 v6, 0, v6
	v_and_b32_e32 v140, 15, v10
	v_lshlrev_b64 v[2:3], s10, v[2:3]
	v_min_u32_e32 v6, s12, v6
	v_mov_b32_e32 v7, v1
	v_bitop3_b32 v8, v15, v140, 7 bitop3:0x6c
	v_lshl_add_u64 v[2:3], v[2:3], 1, s[0:1]
	v_lshlrev_b32_e32 v4, 1, v5
	v_mov_b32_e32 v5, v1
	s_add_i32 s14, s88, s38
	v_lshlrev_b64 v[6:7], s10, v[6:7]
	v_lshl_add_u64 v[2:3], v[2:3], 0, v[4:5]
	s_mov_b32 m0, s14
	v_lshl_add_u64 v[6:7], v[6:7], 1, s[42:43]
	v_lshlrev_b32_e32 v8, 4, v8
	v_mov_b32_e32 v9, v1
	global_load_lds_dwordx4 v[2:3], off
	v_lshl_add_u64 v[6:7], v[6:7], 0, v[8:9]
	s_or_b32 s25, s38, 0x400
	s_add_i32 m0, s13, 0x400
	v_lshl_add_u64 v[2:3], v[2:3], 0, s[70:71]
	global_load_lds_dwordx4 v[6:7], off
	s_add_i32 m0, s88, s25
	v_add_u32_e32 v6, s40, v15
	global_load_lds_dwordx4 v[2:3], off
	v_add_u32_e32 v2, s40, v14
	v_max_i32_e32 v2, 0, v2
	v_min_u32_e32 v2, s12, v2
	v_mov_b32_e32 v3, v1
	v_lshlrev_b64 v[2:3], s10, v[2:3]
	v_lshl_add_u64 v[2:3], v[2:3], 1, s[42:43]
	v_lshl_add_u64 v[2:3], v[2:3], 0, v[0:1]
	s_add_i32 m0, s13, 0x4000
	v_max_i32_e32 v6, 0, v6
	global_load_lds_dwordx4 v[2:3], off
	v_add_u32_e32 v2, s40, v12
	v_max_i32_e32 v2, 0, v2
	v_min_u32_e32 v2, s12, v2
	v_mov_b32_e32 v3, v1
	v_lshlrev_b64 v[2:3], s10, v[2:3]
	v_min_u32_e32 v6, s12, v6
	v_mov_b32_e32 v7, v1
	v_lshl_add_u64 v[2:3], v[2:3], 1, s[0:1]
	v_lshlrev_b64 v[6:7], s10, v[6:7]
	v_lshl_add_u64 v[2:3], v[2:3], 0, v[4:5]
	s_add_i32 m0, s89, s38
	v_lshl_add_u64 v[6:7], v[6:7], 1, s[42:43]
	global_load_lds_dwordx4 v[2:3], off
	v_lshl_add_u64 v[6:7], v[6:7], 0, v[8:9]
	s_add_i32 m0, s13, 0x4400
	v_lshl_add_u64 v[2:3], v[2:3], 0, s[70:71]
	global_load_lds_dwordx4 v[6:7], off
	s_add_i32 m0, s89, s25
	v_lshlrev_b32_e32 v6, 4, v10
	global_load_lds_dwordx4 v[2:3], off
	v_cvt_f32_ubyte0_e32 v2, s21
	v_exp_f32_e64 v2, -v2
	v_cvt_f32_ubyte0_e32 v3, s15
	s_and_b32 s15, s23, 0x3fffffc0
	s_lshl_b32 s15, s15, 2
	v_mul_f32_e32 v2, v2, v3
	v_mul_f32_e32 v143, 0xbfb8aa3b, v2
	v_and_b32_e32 v2, 63, v10
	v_lshlrev_b32_e32 v3, 1, v10
	v_and_b32_e32 v7, 0xc0, v6
	v_lshlrev_b32_e32 v10, 8, v141
	v_and_b32_e32 v6, 0x70, v6
	v_or_b32_e32 v12, 32, v130
	s_add_i32 s15, s15, 0
	v_bitop3_b32 v146, v12, v10, v6 bitop3:0xde
	v_or_b32_e32 v12, 64, v130
	s_ashr_i32 s23, s23, 7
	s_add_i32 s15, s15, 0x20000
	v_bitop3_b32 v148, v12, v10, v6 bitop3:0xde
	v_or_b32_e32 v12, 0x60, v130
	s_add_i32 s25, s23, 2
	v_bitop3_b32 v145, v130, v10, v6 bitop3:0xde
	v_bitop3_b32 v149, v12, v10, v6 bitop3:0xde
	v_and_b32_e32 v6, 0x118, v13
	s_cmp_lg_u32 s88, -1
	v_lshl_add_u64 v[134:135], s[42:43], 0, v[0:1]
	v_lshl_add_u64 v[136:137], s[42:43], 0, v[8:9]
	v_and_or_b32 v0, v3, 32, v6
	s_cselect_b32 s42, s88, 0
	s_add_i32 s37, s37, s40
	v_mov_b32_e32 v14, v1
	v_mov_b32_e32 v15, v1
	s_waitcnt vmcnt(0)
	s_barrier
;     ...
;   if constexpr (DIL) {
;     const int rlo = wid >> 1;
;     for (int j = 0; j < NT; ++j) {
;       if (j + 2 < NT) DMA(j + 2, (j + 2) & 3);
	v_cmp_gt_u32_e64 s[38:39], 32, v2
	v_add3_u32 v150, v7, s42, v0
	v_lshl_add_u64 v[138:139], s[0:1], 0, v[4:5]
	v_or_b32_e32 v152, s37, v11
	v_mov_b32_e32 v0, v1
	v_mov_b32_e32 v2, v1
	v_mov_b32_e32 v3, v1
	v_mov_b32_e32 v4, v1
	v_mov_b32_e32 v6, v1
	v_mov_b32_e32 v7, v1
	v_mov_b32_e32 v8, v1
	v_mov_b32_e32 v10, v1
	v_mov_b32_e32 v11, v1
	v_mov_b32_e32 v12, v1
	v_mov_b32_e32 v13, v1
	v_mov_b64_e32 v[64:65], v[14:15]
	v_mov_b64_e32 v[48:49], v[14:15]
	v_mov_b64_e32 v[32:33], v[14:15]
	v_mov_b64_e32 v[62:63], v[12:13]
	v_mov_b64_e32 v[60:61], v[10:11]
	v_mov_b64_e32 v[58:59], v[8:9]
	v_mov_b64_e32 v[56:57], v[6:7]
	v_mov_b64_e32 v[54:55], v[4:5]
	v_mov_b64_e32 v[52:53], v[2:3]
	v_mov_b64_e32 v[50:51], v[0:1]
	v_mov_b64_e32 v[46:47], v[12:13]
	v_mov_b64_e32 v[44:45], v[10:11]
	v_mov_b64_e32 v[42:43], v[8:9]
	v_mov_b64_e32 v[40:41], v[6:7]
	v_mov_b64_e32 v[38:39], v[4:5]
	v_mov_b64_e32 v[36:37], v[2:3]
	v_mov_b64_e32 v[34:35], v[0:1]
	v_mov_b64_e32 v[30:31], v[12:13]
	v_mov_b64_e32 v[28:29], v[10:11]
	v_mov_b64_e32 v[26:27], v[8:9]
	v_mov_b64_e32 v[24:25], v[6:7]
	v_mov_b64_e32 v[22:23], v[4:5]
	v_mov_b64_e32 v[20:21], v[2:3]
	v_mov_b64_e32 v[18:19], v[0:1]
	v_mov_b64_e32 v[16:17], v[14:15]
	s_cmp_gt_u32 s23, 1
	s_cselect_b32 s80, 1, 0
	s_sub_i32 s80, s23, s80
	s_lshl_b32 s21, s80, 14
	v_lshl_add_u32 v147, v141, 2, s15
	v_or_b32_e32 v151, s37, v131
	v_mov_b32_e32 v153, 0
	v_mov_b32_e32 v144, 0xf149f2ca
	s_lshl_b32 s37, s80, 6
	s_addk_i32 s37, 0xffc0
	v_mov_b64_e32 v[14:15], v[12:13]
	v_mov_b64_e32 v[12:13], v[10:11]
	v_mov_b64_e32 v[10:11], v[8:9]
	v_mov_b64_e32 v[8:9], v[6:7]
	v_mov_b64_e32 v[6:7], v[4:5]
	v_mov_b64_e32 v[4:5], v[2:3]
	v_mov_b64_e32 v[2:3], v[0:1]
	s_mov_b32 s46, s80
	s_movk_i32 s83, 0xffc0
	s_mov_b32 s84, 0
	v_add_u32_e32 v68, s83, v151
	v_add_u32_e32 v0, 0x80, v68
	v_max_i32_e32 v0, 0, v0
	v_min_i32_e32 v0, s12, v0
	s_add_i32 s0, s84, 0x8000
	v_lshlrev_b64 v[66:67], s10, v[0:1]
	v_add_u32_e32 v0, s83, v152
	s_and_b32 s0, s0, 0xc000
	v_add_u32_e32 v0, 0x80, v0
	s_add_i32 s1, s13, s0
	v_max_i32_e32 v0, 0, v0
	v_lshl_add_u64 v[66:67], v[66:67], 1, v[134:135]
	s_mov_b32 m0, s1
	v_min_i32_e32 v0, s12, v0
	global_load_lds_dwordx4 v[66:67], off
	v_lshlrev_b64 v[66:67], s10, v[0:1]
	v_add_u32_e32 v0, 0x84, v68
	v_max_i32_e32 v0, 0, v0
	s_add_i32 s0, s14, s0
	v_min_i32_e32 v0, s12, v0
	v_lshl_add_u64 v[66:67], v[66:67], 1, v[138:139]
	s_mov_b32 m0, s0
	v_lshlrev_b64 v[68:69], s10, v[0:1]
	global_load_lds_dwordx4 v[66:67], off
	v_lshl_add_u64 v[68:69], v[68:69], 1, v[136:137]
	s_add_i32 m0, s1, 0x400
	v_lshl_add_u64 v[66:67], v[66:67], 0, s[70:71]
	global_load_lds_dwordx4 v[68:69], off
	s_add_i32 m0, s0, 0x400
	s_nop 0
	global_load_lds_dwordx4 v[66:67], off
	s_mov_b32 s83, 0
	s_movk_i32 s84, 0x4000
	v_add_u32_e32 v68, s83, v151
	v_add_u32_e32 v0, 0x80, v68
	v_max_i32_e32 v0, 0, v0
	v_min_i32_e32 v0, s12, v0
	s_add_i32 s0, s84, 0x8000
	v_lshlrev_b64 v[66:67], s10, v[0:1]
	v_add_u32_e32 v0, s83, v152
	s_and_b32 s0, s0, 0xc000
	v_add_u32_e32 v0, 0x80, v0
	s_add_i32 s1, s13, s0
	v_max_i32_e32 v0, 0, v0
	v_lshl_add_u64 v[66:67], v[66:67], 1, v[134:135]
	s_mov_b32 m0, s1
	v_min_i32_e32 v0, s12, v0
	global_load_lds_dwordx4 v[66:67], off
	v_lshlrev_b64 v[66:67], s10, v[0:1]
	v_add_u32_e32 v0, 0x84, v68
	v_max_i32_e32 v0, 0, v0
	s_add_i32 s0, s14, s0
	v_min_i32_e32 v0, s12, v0
	v_lshl_add_u64 v[66:67], v[66:67], 1, v[138:139]
	s_mov_b32 m0, s0
	v_lshlrev_b64 v[68:69], s10, v[0:1]
	global_load_lds_dwordx4 v[66:67], off
	v_lshl_add_u64 v[68:69], v[68:69], 1, v[136:137]
	s_add_i32 m0, s1, 0x400
	v_lshl_add_u64 v[66:67], v[66:67], 0, s[70:71]
	global_load_lds_dwordx4 v[68:69], off
	s_add_i32 m0, s0, 0x400
	s_nop 0
	global_load_lds_dwordx4 v[66:67], off
	s_mov_b32 s82, 0
	s_branch .LBB0_140
.LBB0_139:
	s_addk_i32 s21, 0x4000
	s_add_i32 s37, s37, 64
	s_add_i32 s46, s46, 1
	s_add_i32 s82, s82, 1
	s_add_i32 s83, s83, 64
	s_addk_i32 s84, 0x4000
	s_cmpk_eq_i32 s82, 4
	s_cbranch_scc1 .LBB0_153
.LBB0_140:
	s_sub_i32 s80, s82, 1
	s_cmp_gt_u32 s80, 1
	s_cbranch_scc1 .LBB0_142
	v_add_u32_e32 v68, s83, v151
	v_add_u32_e32 v0, 0x80, v68
	v_max_i32_e32 v0, 0, v0
	v_min_i32_e32 v0, s12, v0
	s_add_i32 s0, s84, 0x8000
	v_lshlrev_b64 v[66:67], s10, v[0:1]
	v_add_u32_e32 v0, s83, v152
	s_and_b32 s0, s0, 0xc000
	v_add_u32_e32 v0, 0x80, v0
	s_add_i32 s1, s13, s0
	v_max_i32_e32 v0, 0, v0
	v_lshl_add_u64 v[66:67], v[66:67], 1, v[134:135]
	s_mov_b32 m0, s1
	v_min_i32_e32 v0, s12, v0
	global_load_lds_dwordx4 v[66:67], off
	v_lshlrev_b64 v[66:67], s10, v[0:1]
	v_add_u32_e32 v0, 0x84, v68
	v_max_i32_e32 v0, 0, v0
	s_add_i32 s0, s14, s0
	v_min_i32_e32 v0, s12, v0
	v_lshl_add_u64 v[66:67], v[66:67], 1, v[138:139]
	s_mov_b32 m0, s0
	v_lshlrev_b64 v[68:69], s10, v[0:1]
	global_load_lds_dwordx4 v[66:67], off
	v_lshl_add_u64 v[68:69], v[68:69], 1, v[136:137]
	s_add_i32 m0, s1, 0x400
	v_lshl_add_u64 v[66:67], v[66:67], 0, s[70:71]
	global_load_lds_dwordx4 v[68:69], off
	s_add_i32 m0, s0, 0x400
	s_nop 0
	global_load_lds_dwordx4 v[66:67], off

; #define SBAR() __builtin_amdgcn_sched_barrier(0)
; #define ENDSTEP(j) do { if ((j) + 2 < NT) asm volatile("s_waitcnt vmcnt(4) lgkmcnt(0)\n\ts_barrier" ::: "memory"); else asm volatile("s_waitcnt vmcnt(0) lgkmcnt(0)\n\ts_barrier" ::: "memory"); } while (0)
; #define RESC(a) do { if (__any((a) < 1.f)) { if (hi == 0) al_l[r32] = (a); asm volatile("s_waitcnt lgkmcnt(0)" ::: "memory"); \
;     for (int d = 0; d < 4; ++d) for (int r = 0; r < 16; ++r) o[d][r] *= al_l[crow(r, hi)]; } } while (0)
; #define PSM(P0, P1, MN, AL, jt) do { if constexpr (DIL) { const int t_ = otid(), iq_ = (t_ >> 6) * QBLK + (t_ & 31), hi_ = (t_ >> 5) & 1; \
;       partialSM_dil(P0, P1, m_reg, MN, AL, (float)(-64 - iq_ + 4 * hi_ + 64 * (jt)), fmaxf(-64.f, (float)(-(i0 + iq_))), fminf(64.f, (float)(nsub - 1 - (i0 + iq_))), nslopeC); } \
;     else partialSM(P0, P1, m_reg, MN, AL); } while (0)
; #define KRD(f, d0, kb) asm volatile("ds_read_b128 %0, %2 offset:%3\n\tds_read_b128 %1, %2 offset:%4" : "=&v"(f.a), "=&v"(f.b) : "v"((kb) + koff[(d0) & 3]), "i"(((d0) >> 2) * 128), "i"(((d0) >> 2) * 128 + 8192) : "memory")
; #define QMM(f, d0) do { pA0 = __builtin_amdgcn_mfma_f32_32x32x16_bf16(f.a, qr[d0], pA0, 0, 0, 0); pA1 = __builtin_amdgcn_mfma_f32_32x32x16_bf16(f.b, qr[d0], pA1, 0, 0, 0); } while (0)
; #define LW(n) do { asm volatile("s_waitcnt lgkmcnt(" #n ")" ::: "memory"); SBAR(); } while (0)
;     ...
;     for (int j = 0; j < NT; ++j) {
;       if (j + 2 < NT) DMA(j + 2, (j + 2) & 3);
;       if (j >= rlo && j <= rlo + 2) {
;         SBAR();
;         { const int kb_ = kbase0 + (j & 3) * (int)SHM_K; KFrag k0_, k1_, k2_;
;           KRD(k0_, 0, kb_); KRD(k1_, 1, kb_); KRD(k2_, 2, kb_); pA0 = f32x16{}; pA1 = f32x16{};
;           LW(4); QMM(k0_, 0); SBAR(); KRD(k0_, 3, kb_);
;           LW(4); QMM(k1_, 1); SBAR(); KRD(k1_, 4, kb_);
;           LW(4); QMM(k2_, 2); SBAR(); KRD(k2_, 5, kb_);
;           LW(4); QMM(k0_, 3); SBAR(); KRD(k0_, 6, kb_);
;           LW(4); QMM(k1_, 4); SBAR(); KRD(k1_, 7, kb_);
;           LW(4); QMM(k2_, 5); SBAR();
;           LW(2); QMM(k0_, 6); SBAR();
;           LW(0); QMM(k1_, 7); SBAR(); }
;         PSM(pA0, pA1, mnA, alA, j); RESC(alA);
;         finishSM(pA0, pA1, alA, l_reg, pa0, pa1, pa2, pa3); SBAR();
;         pv_d0(o, VBUF(j), pa0, pa1, pa2, pa3);
;       }
;       if (j + 1 < NT) ENDSTEP(j);
.LBB0_148:
	s_cmpk_eq_i32 s82, 3
	s_cbranch_scc1 .LBB0_139
	s_waitcnt vmcnt(0) lgkmcnt(0)
	s_barrier
	s_branch .LBB0_139
